# sweep 2 far tiles: QK operand reads re-ordered by need (extra K buffers, second-half K reads last, counted waits)
# baseline (speedup 1.0000x reference)
; template <bool DIFF>
; __device__ __forceinline__ void qkt(f32x16& a, f32x16& b, const char* Ks, const char* Qs, int krow, int r32, int hi) {
;   a = f32x16{}; b = f32x16{};
; #pragma unroll
;   for (int d = 0; d < 4; ++d) {
;     const int cb0 = (d * 16 + hi * 8) * 2, cb1 = ((d + 4) * 16 + hi * 8) * 2;
;     const bf16x8 k0 = *reinterpret_cast<const bf16x8*>(Ks + KSWZ(krow, cb0)), q0 = *reinterpret_cast<const bf16x8*>(Qs + KSWZ(r32, cb0));
;     const bf16x8 k1 = *reinterpret_cast<const bf16x8*>(Ks + KSWZ(krow, cb1)), q1 = *reinterpret_cast<const bf16x8*>(Qs + KSWZ(r32, cb1));
;     a = __builtin_amdgcn_mfma_f32_32x32x16_bf16(k0, q0, a, 0, 0, 0);
;     b = __builtin_amdgcn_mfma_f32_32x32x16_bf16(k1, q1, b, 0, 0, 0); }
; template <bool DIFF> ...
;     ...
;       BIAS_APPLY(t, 0, a0, b0, cb0);
;       { const float x1 = fmaf(cb0, C, e1), x2 = fmaf(cb0, C, e2);
; #pragma unroll
;       for (int r = 0; r < 16; ++r) a0[r] = __builtin_amdgcn_exp2f(fmaf(a0[r], C, x1));
;       if (DIFF) {
; #pragma unroll
;         for (int r = 0; r < 16; ++r) a0[r] = fmaf(nsg, __builtin_amdgcn_exp2f(fmaf(b0[r], C, x2)), a0[r]);
;       } }
.Lsw2f:
	ds_read_b128 v[238:241], v176
	ds_read_b128 v[68:71], v172 offset:36864
	ds_read_b128 v[72:75], v177
	ds_read_b128 v[64:67], v171 offset:36864
	ds_read_b128 v[80:83], v179
	ds_read_b128 v[140:143], v169 offset:36864
	ds_read_b128 v[242:245], v178
	ds_read_b128 v[132:135], v170 offset:36864
	ds_read_b128 v[246:249], v181
	ds_read_b128 v[204:207], v167 offset:36864
	s_waitcnt lgkmcnt(8)
	v_mfma_f32_32x32x16_bf16 v[112:127], v[238:241], v[68:71], 0
	ds_read_b128 v[238:241], v180
	ds_read_b128 v[196:199], v168 offset:36864
	s_waitcnt lgkmcnt(8)
	v_mfma_f32_32x32x16_bf16 v[96:111], v[72:75], v[64:67], 0
	ds_read_b128 v[72:75], v183
	ds_read_b128 v[222:225], v149 offset:36864
	s_waitcnt lgkmcnt(8)
	v_mfma_f32_32x32x16_bf16 v[96:111], v[80:83], v[140:143], v[96:111]
	ds_read_b128 v[80:83], v182
	ds_read_b128 v[214:217], v166 offset:36864
	s_waitcnt lgkmcnt(8)
	v_mfma_f32_32x32x16_bf16 v[112:127], v[242:245], v[132:135], v[112:127]
	ds_read_b128 v[76:79], v176 offset:8192
	ds_read_b128 v[128:131], v177 offset:8192
	ds_read_b128 v[136:139], v178 offset:8192
	ds_read_b128 v[192:195], v179 offset:8192
	ds_read_b128 v[200:203], v180 offset:8192
	ds_read_b128 v[210:213], v181 offset:8192
	ds_read_b128 v[218:221], v182 offset:8192
	ds_read_b128 v[226:229], v183 offset:8192
	s_waitcnt lgkmcnt(14)
	v_mfma_f32_32x32x16_bf16 v[96:111], v[246:249], v[204:207], v[96:111]
	s_waitcnt lgkmcnt(12)
	v_mfma_f32_32x32x16_bf16 v[112:127], v[238:241], v[196:199], v[112:127]
	s_waitcnt lgkmcnt(10)
	v_mfma_f32_32x32x16_bf16 v[96:111], v[72:75], v[222:225], v[96:111]
	s_waitcnt lgkmcnt(8)
	v_mfma_f32_32x32x16_bf16 v[112:127], v[80:83], v[214:217], v[112:127]
	s_waitcnt lgkmcnt(7)
	v_mfma_f32_32x32x16_bf16 v[80:95], v[76:79], v[68:71], 0
	v_fmamk_f32 v235, v234, 0x3e38aa3b, v188
	v_fmamk_f32 v234, v234, 0x3e38aa3b, v187
	s_nop 8
	v_fmamk_f32 v112, v112, 0x3e38aa3b, v235
	v_fmamk_f32 v113, v113, 0x3e38aa3b, v235
	v_fmamk_f32 v114, v114, 0x3e38aa3b, v235
	v_fmamk_f32 v115, v115, 0x3e38aa3b, v235
	v_fmamk_f32 v116, v116, 0x3e38aa3b, v235
	v_fmamk_f32 v117, v117, 0x3e38aa3b, v235
	v_fmamk_f32 v96, v96, 0x3e38aa3b, v234
	v_fmamk_f32 v97, v97, 0x3e38aa3b, v234
	v_fmamk_f32 v98, v98, 0x3e38aa3b, v234
	v_fmamk_f32 v99, v99, 0x3e38aa3b, v234
	v_fmamk_f32 v100, v100, 0x3e38aa3b, v234
	v_fmamk_f32 v101, v101, 0x3e38aa3b, v234
	v_exp_f32_e32 v112, v112
	s_waitcnt lgkmcnt(6)
	v_mfma_f32_32x32x16_bf16 v[64:79], v[128:131], v[64:67], 0
	v_exp_f32_e32 v113, v113
	v_exp_f32_e32 v114, v114
	v_exp_f32_e32 v115, v115
	v_exp_f32_e32 v116, v116
	v_exp_f32_e32 v117, v117
	v_fmamk_f32 v118, v118, 0x3e38aa3b, v235
	v_fmamk_f32 v119, v119, 0x3e38aa3b, v235
	v_fmamk_f32 v120, v120, 0x3e38aa3b, v235
	v_fmamk_f32 v121, v121, 0x3e38aa3b, v235
	v_fmamk_f32 v122, v122, 0x3e38aa3b, v235
	s_waitcnt lgkmcnt(5)
	v_mfma_f32_32x32x16_bf16 v[80:95], v[136:139], v[132:135], v[80:95]
	v_fmamk_f32 v123, v123, 0x3e38aa3b, v235
	v_fmamk_f32 v124, v124, 0x3e38aa3b, v235
	v_fmamk_f32 v125, v125, 0x3e38aa3b, v235
	v_fmamk_f32 v126, v126, 0x3e38aa3b, v235
	v_fmac_f32_e32 v235, 0x3e38aa3b, v127
	v_exp_f32_e32 v96, v96
	v_exp_f32_e32 v97, v97
	v_exp_f32_e32 v98, v98
	v_exp_f32_e32 v99, v99
	v_exp_f32_e32 v100, v100
	v_exp_f32_e32 v101, v101
	s_waitcnt lgkmcnt(4)
	v_mfma_f32_32x32x16_bf16 v[64:79], v[192:195], v[140:143], v[64:79]
	v_lshl_add_u64 v[128:129], v[150:151], 0, s[34:35]
	v_add_co_u32_e32 v130, vcc, s70, v128
	s_nop 1
	v_addc_co_u32_e32 v131, vcc, 0, v129, vcc
	v_add_co_u32_e32 v132, vcc, s71, v128
	v_lshl_add_u64 v[136:137], v[152:153], 0, s[34:35]
	s_nop 0
	v_addc_co_u32_e32 v133, vcc, 0, v129, vcc
	v_add_co_u32_e32 v138, vcc, s72, v136
	s_nop 1
	v_addc_co_u32_e32 v139, vcc, 0, v137, vcc
	v_add_co_u32_e32 v140, vcc, s73, v136
	global_load_dwordx4 v[128:131], v[130:131], off
	s_nop 0
	global_load_dwordx4 v[132:135], v[132:133], off
	v_addc_co_u32_e32 v141, vcc, 0, v137, vcc
	global_load_dwordx4 v[136:139], v[138:139], off
	s_nop 0
	global_load_dwordx4 v[140:143], v[140:141], off
	v_fmamk_f32 v102, v102, 0x3e38aa3b, v234
	v_fmamk_f32 v103, v103, 0x3e38aa3b, v234
	v_fmamk_f32 v104, v104, 0x3e38aa3b, v234
	v_fmamk_f32 v105, v105, 0x3e38aa3b, v234
	v_fmamk_f32 v106, v106, 0x3e38aa3b, v234
	v_fmamk_f32 v107, v107, 0x3e38aa3b, v234
	v_fmamk_f32 v108, v108, 0x3e38aa3b, v234
	v_fmamk_f32 v109, v109, 0x3e38aa3b, v234
	v_fmamk_f32 v110, v110, 0x3e38aa3b, v234
	v_fmac_f32_e32 v234, 0x3e38aa3b, v111
	v_exp_f32_e32 v118, v118
	v_exp_f32_e32 v119, v119
	v_exp_f32_e32 v120, v120
	s_waitcnt lgkmcnt(3)
	v_mfma_f32_32x32x16_bf16 v[80:95], v[200:203], v[196:199], v[80:95]
	v_exp_f32_e32 v121, v121
	v_exp_f32_e32 v122, v122
	v_exp_f32_e32 v123, v123
	v_exp_f32_e32 v124, v124
	v_exp_f32_e32 v125, v125
	v_exp_f32_e32 v126, v126
	v_exp_f32_e32 v127, v235
	v_exp_f32_e32 v102, v102
	s_waitcnt lgkmcnt(2)
	v_mfma_f32_32x32x16_bf16 v[64:79], v[210:213], v[204:207], v[64:79]
	v_exp_f32_e32 v103, v103
	v_exp_f32_e32 v104, v104
	v_exp_f32_e32 v105, v105
	v_exp_f32_e32 v106, v106
	v_exp_f32_e32 v107, v107
	v_exp_f32_e32 v108, v108
	v_exp_f32_e32 v109, v109
	v_exp_f32_e32 v110, v110
	s_waitcnt lgkmcnt(1)
	v_mfma_f32_32x32x16_bf16 v[80:95], v[218:221], v[214:217], v[80:95]
	v_exp_f32_e32 v111, v234
	v_pk_fma_f32 v[96:97], v[144:145], v[96:97], v[112:113]
	v_pk_fma_f32 v[98:99], v[144:145], v[98:99], v[114:115]
	v_pk_fma_f32 v[100:101], v[144:145], v[100:101], v[116:117]
	v_pk_fma_f32 v[102:103], v[144:145], v[102:103], v[118:119]
	v_pk_fma_f32 v[104:105], v[144:145], v[104:105], v[120:121]
	v_pk_fma_f32 v[106:107], v[144:145], v[106:107], v[122:123]
	v_pk_fma_f32 v[108:109], v[144:145], v[108:109], v[124:125]
	s_waitcnt lgkmcnt(0)
; #define SBAR() __builtin_amdgcn_sched_barrier(0)
; template <int KS> __device__ __forceinline__ void pv_step(f32x16* o, int vb, bf16x8 pa) {
;   const s16x4 l0 = tr_read<v_rd_off(0, KS, 0)>(vb), h0 = tr_read<v_rd_off(0, KS, 1)>(vb), l1 = tr_read<v_rd_off(1, KS, 0)>(vb), h1 = tr_read<v_rd_off(1, KS, 1)>(vb);
;   const s16x4 l2 = tr_read<v_rd_off(2, KS, 0)>(vb), h2 = tr_read<v_rd_off(2, KS, 1)>(vb), l3 = tr_read<v_rd_off(3, KS, 0)>(vb), h3 = tr_read<v_rd_off(3, KS, 1)>(vb);
;   asm volatile("s_waitcnt lgkmcnt(0)" ::: "memory"); SBAR();
;     ...
;   o[0] = __builtin_amdgcn_mfma_f32_32x32x16_bf16(pa, PK(l0, h0), o[0], 0, 0, 0);
;   o[1] = __builtin_amdgcn_mfma_f32_32x32x16_bf16(pa, PK(l1, h1), o[1], 0, 0, 0);
;   o[2] = __builtin_amdgcn_mfma_f32_32x32x16_bf16(pa, PK(l2, h2), o[2], 0, 0, 0);
;   o[3] = __builtin_amdgcn_mfma_f32_32x32x16_bf16(pa, PK(l3, h3), o[3], 0, 0, 0);
;     ...
; }
; template <bool DIFF> ...
;     ...
;       PK4(a0, 0, pa0); PK4(a0, 8, pa1);
;       SBAR();
;       pv_step<0>(o, vb0, pa0); pv_step<1>(o, vb0, pa1);
;       SBAR();
;       BIAS_APPLY(t, 1, a1, b1, cb1);
;       { const float x1 = fmaf(cb1, C, e1), x2 = fmaf(cb1, C, e2);
; #pragma unroll
;       for (int r = 0; r < 16; ++r) a1[r] = __builtin_amdgcn_exp2f(fmaf(a1[r], C, x1));
;       if (DIFF) {
; #pragma unroll
;         for (int r = 0; r < 16; ++r) a1[r] = fmaf(nsg, __builtin_amdgcn_exp2f(fmaf(b1[r], C, x2)), a1[r]);
;       } }
;       PK4(a1, 0, pa2); PK4(a1, 8, pa3);
;       SBAR();
;       pv_step<2>(o, vb0, pa2); pv_step<3>(o, vb0, pa3);
	v_mfma_f32_32x32x16_bf16 v[64:79], v[226:229], v[222:225], v[64:79]
	v_pk_fma_f32 v[110:111], v[144:145], v[110:111], v[126:127]
	v_cvt_pk_bf16_f32 v96, v96, v97
	v_cvt_pk_bf16_f32 v97, v98, v99
	v_cvt_pk_bf16_f32 v98, v100, v101
	v_cvt_pk_bf16_f32 v99, v102, v103
	s_nop 0
	v_permlane32_swap_b32_e32 v96, v98
	v_cvt_pk_bf16_f32 v100, v104, v105
	v_cvt_pk_bf16_f32 v101, v106, v107
	v_cvt_pk_bf16_f32 v102, v108, v109
	v_cvt_pk_bf16_f32 v103, v110, v111
	v_permlane32_swap_b32_e32 v97, v99
	v_permlane32_swap_b32_e32 v100, v102
	v_permlane32_swap_b32_e32 v101, v103
	ds_read_b64_tr_b16 v[104:105], v146 offset:0
	ds_read_b64_tr_b16 v[106:107], v146 offset:0x800
	ds_read_b64_tr_b16 v[108:109], v146 offset:0x200
	ds_read_b64_tr_b16 v[110:111], v146 offset:0xa00
	ds_read_b64_tr_b16 v[112:113], v146 offset:0x400
	ds_read_b64_tr_b16 v[114:115], v146 offset:0xc00
	ds_read_b64_tr_b16 v[116:117], v146 offset:0x600
	ds_read_b64_tr_b16 v[118:119], v146 offset:0xe00
	ds_read_b64_tr_b16 v[238:239], v146 offset:0x1000
	ds_read_b64_tr_b16 v[240:241], v146 offset:0x1800
	ds_read_b64_tr_b16 v[242:243], v146 offset:0x1200
	ds_read_b64_tr_b16 v[244:245], v146 offset:0x1a00
	ds_read_b64_tr_b16 v[246:247], v146 offset:0x1400
	ds_read_b64_tr_b16 v[248:249], v146 offset:0x1c00
	ds_read_b64_tr_b16 v[120:121], v146 offset:0x1600
	ds_read_b64_tr_b16 v[122:123], v146 offset:0x1e00
	v_fmamk_f32 v237, v236, 0x3e38aa3b, v188
	v_fmamk_f32 v236, v236, 0x3e38aa3b, v187
	v_fmamk_f32 v80, v80, 0x3e38aa3b, v237
	v_fmamk_f32 v81, v81, 0x3e38aa3b, v237
	v_fmamk_f32 v82, v82, 0x3e38aa3b, v237
	v_fmamk_f32 v83, v83, 0x3e38aa3b, v237
	v_fmamk_f32 v84, v84, 0x3e38aa3b, v237
	v_fmamk_f32 v85, v85, 0x3e38aa3b, v237
	v_fmamk_f32 v86, v86, 0x3e38aa3b, v237
	v_fmamk_f32 v87, v87, 0x3e38aa3b, v237
	s_waitcnt lgkmcnt(0)
	ds_read_b64_tr_b16 v[192:193], v146 offset:0x2000
	ds_read_b64_tr_b16 v[194:195], v146 offset:0x2800
	ds_read_b64_tr_b16 v[196:197], v146 offset:0x2200
	ds_read_b64_tr_b16 v[198:199], v146 offset:0x2a00
	ds_read_b64_tr_b16 v[200:201], v146 offset:0x2400
	ds_read_b64_tr_b16 v[202:203], v146 offset:0x2c00
	ds_read_b64_tr_b16 v[204:205], v146 offset:0x2600
	ds_read_b64_tr_b16 v[206:207], v146 offset:0x2e00
	ds_read_b64_tr_b16 v[210:211], v146 offset:0x3000
	ds_read_b64_tr_b16 v[212:213], v146 offset:0x3800
	ds_read_b64_tr_b16 v[214:215], v146 offset:0x3200
	ds_read_b64_tr_b16 v[216:217], v146 offset:0x3a00
	ds_read_b64_tr_b16 v[218:219], v146 offset:0x3400
	ds_read_b64_tr_b16 v[220:221], v146 offset:0x3c00
	ds_read_b64_tr_b16 v[222:223], v146 offset:0x3600
	ds_read_b64_tr_b16 v[224:225], v146 offset:0x3e00
	v_mfma_f32_32x32x16_bf16 v[0:15], v[96:99], v[104:107], v[0:15]
	v_fmamk_f32 v88, v88, 0x3e38aa3b, v237
	v_fmamk_f32 v89, v89, 0x3e38aa3b, v237
	v_fmamk_f32 v90, v90, 0x3e38aa3b, v237
	v_fmamk_f32 v91, v91, 0x3e38aa3b, v237
	v_fmamk_f32 v92, v92, 0x3e38aa3b, v237
	v_fmamk_f32 v93, v93, 0x3e38aa3b, v237
	v_fmamk_f32 v94, v94, 0x3e38aa3b, v237
	v_fmac_f32_e32 v237, 0x3e38aa3b, v95
	v_fmamk_f32 v64, v64, 0x3e38aa3b, v236
	v_fmamk_f32 v65, v65, 0x3e38aa3b, v236
	v_fmamk_f32 v66, v66, 0x3e38aa3b, v236
	v_fmamk_f32 v67, v67, 0x3e38aa3b, v236
	v_fmamk_f32 v68, v68, 0x3e38aa3b, v236
	v_fmamk_f32 v69, v69, 0x3e38aa3b, v236
	v_fmamk_f32 v70, v70, 0x3e38aa3b, v236
	v_mfma_f32_32x32x16_bf16 v[16:31], v[96:99], v[108:111], v[16:31]
	v_fmamk_f32 v71, v71, 0x3e38aa3b, v236
	v_fmamk_f32 v72, v72, 0x3e38aa3b, v236
	v_fmamk_f32 v73, v73, 0x3e38aa3b, v236
	v_fmamk_f32 v74, v74, 0x3e38aa3b, v236
	v_fmamk_f32 v75, v75, 0x3e38aa3b, v236
	v_fmamk_f32 v76, v76, 0x3e38aa3b, v236
	v_fmamk_f32 v77, v77, 0x3e38aa3b, v236
	v_fmamk_f32 v78, v78, 0x3e38aa3b, v236
	v_fmac_f32_e32 v236, 0x3e38aa3b, v79
	v_exp_f32_e32 v80, v80
	v_exp_f32_e32 v81, v81
	v_exp_f32_e32 v82, v82
	v_mfma_f32_32x32x16_bf16 v[32:47], v[96:99], v[112:115], v[32:47]
	v_exp_f32_e32 v83, v83
	v_exp_f32_e32 v84, v84
	v_exp_f32_e32 v85, v85
	v_exp_f32_e32 v86, v86
	v_exp_f32_e32 v87, v87
	v_exp_f32_e32 v88, v88
	v_exp_f32_e32 v89, v89
	v_mfma_f32_32x32x16_bf16 v[48:63], v[96:99], v[116:119], v[48:63]
	v_exp_f32_e32 v90, v90
	v_exp_f32_e32 v91, v91
	v_exp_f32_e32 v92, v92
	v_exp_f32_e32 v93, v93
	v_exp_f32_e32 v94, v94
	v_exp_f32_e32 v95, v237
	v_exp_f32_e32 v64, v64
	v_mfma_f32_32x32x16_bf16 v[0:15], v[100:103], v[238:241], v[0:15]
	v_exp_f32_e32 v65, v65
	v_exp_f32_e32 v66, v66
	v_exp_f32_e32 v67, v67
	v_exp_f32_e32 v68, v68
	v_exp_f32_e32 v69, v69
	v_exp_f32_e32 v70, v70
	v_exp_f32_e32 v71, v71
	v_mfma_f32_32x32x16_bf16 v[16:31], v[100:103], v[242:245], v[16:31]
	v_exp_f32_e32 v72, v72
	v_exp_f32_e32 v73, v73
	v_exp_f32_e32 v74, v74
	v_exp_f32_e32 v75, v75
	v_exp_f32_e32 v76, v76
	v_exp_f32_e32 v77, v77
	v_exp_f32_e32 v78, v78
	v_mfma_f32_32x32x16_bf16 v[32:47], v[100:103], v[246:249], v[32:47]
	v_exp_f32_e32 v79, v236
	v_pk_fma_f32 v[64:65], v[144:145], v[64:65], v[80:81]
	v_pk_fma_f32 v[66:67], v[144:145], v[66:67], v[82:83]
	v_pk_fma_f32 v[68:69], v[144:145], v[68:69], v[84:85]
	v_pk_fma_f32 v[70:71], v[144:145], v[70:71], v[86:87]
	v_pk_fma_f32 v[72:73], v[144:145], v[72:73], v[88:89]
	v_pk_fma_f32 v[74:75], v[144:145], v[74:75], v[90:91]
	v_mfma_f32_32x32x16_bf16 v[48:63], v[100:103], v[120:123], v[48:63]
	v_pk_fma_f32 v[76:77], v[144:145], v[76:77], v[92:93]
	v_pk_fma_f32 v[78:79], v[144:145], v[78:79], v[94:95]
	v_cvt_pk_bf16_f32 v64, v64, v65
	v_cvt_pk_bf16_f32 v65, v66, v67
	v_cvt_pk_bf16_f32 v66, v68, v69
	v_cvt_pk_bf16_f32 v67, v70, v71
	v_cvt_pk_bf16_f32 v68, v72, v73
	v_cvt_pk_bf16_f32 v69, v74, v75
	v_cvt_pk_bf16_f32 v70, v76, v77
	v_cvt_pk_bf16_f32 v71, v78, v79
	v_permlane32_swap_b32_e32 v64, v66
	v_permlane32_swap_b32_e32 v65, v67
	v_permlane32_swap_b32_e32 v68, v70
	v_permlane32_swap_b32_e32 v69, v71
	s_waitcnt lgkmcnt(0)
	v_mfma_f32_32x32x16_bf16 v[0:15], v[64:67], v[192:195], v[0:15]
	v_mfma_f32_32x32x16_bf16 v[16:31], v[64:67], v[196:199], v[16:31]
	v_mfma_f32_32x32x16_bf16 v[32:47], v[64:67], v[200:203], v[32:47]
	v_mfma_f32_32x32x16_bf16 v[48:63], v[64:67], v[204:207], v[48:63]
	v_mfma_f32_32x32x16_bf16 v[0:15], v[68:71], v[210:213], v[0:15]
	s_add_u32 s34, s34, 0x20000
	s_addc_u32 s35, s35, 0
	v_add_u32_e32 v173, 64, v173
	s_add_i32 s93, s93, 64
	s_cmp_eq_u32 s2, s34
	v_mfma_f32_32x32x16_bf16 v[16:31], v[68:71], v[214:217], v[16:31]
	v_mfma_f32_32x32x16_bf16 v[32:47], v[68:71], v[218:221], v[32:47]
	v_mfma_f32_32x32x16_bf16 v[48:63], v[68:71], v[222:225], v[48:63]
	s_cbranch_scc1 .LBB0_326
	s_branch .LBB0_310
